# rg_in, gates and sc_in unit-order arithmetic in 32-bit scalar ops as well
# speedup vs baseline: 1.0020x; 1.0020x over previous
.LBB0_107:
	s_add_i32 s76, s76, 1
	s_mul_i32 s7, s76, s72
	s_add_i32 s7, s7, s2
	s_cmp_lt_u32 s7, 0x218
	s_cselect_b64 s[0:1], -1, 0
	s_cbranch_scc0 .LBB0_109
	s_and_b32 s8, s7, 7
	s_lshr_b32 s7, s7, 3
	s_mul_i32 s8, s8, 0x43
	s_add_i32 s7, s8, s7
	s_lshr_b32 s88, s7, 3
	s_and_b32 s86, s7, 7

.LBB0_455:
	s_add_i32 s87, s87, 1
	s_mul_i32 s1, s87, s26
	s_add_i32 s36, s1, s101
	s_mov_b32 s37, 0
	s_cmp_lt_u32 s36, 0x218
	s_cselect_b64 s[44:45], -1, 0
	s_cbranch_scc0 .LBB0_457
	s_and_b32 s1, s36, 7
	s_lshr_b32 s8, s36, 3
	s_mul_i32 s1, s1, 0x43
	s_add_i32 s1, s1, s8
	s_lshr_b32 s56, s1, 3
	s_and_b32 s46, s1, 7

.LBB0_1539:
	s_add_i32 s57, s57, 1
	s_mul_i32 s6, s57, s26
	s_add_i32 s6, s6, s101
	s_cmp_lt_u32 s6, 0x324
	s_cselect_b64 s[0:1], -1, 0
	s_cbranch_scc0 .LBB0_1545
	s_and_b32 s8, s6, 7
	s_lshr_b32 s3, s6, 3
	s_mul_i32 s9, s8, 0x64
	s_min_u32 s8, s8, 4
	s_add_i32 s9, s9, s8
	s_add_i32 s3, s9, s3
	s_mul_hi_u32 s72, s3, 0x2aaaaaab
	s_lshr_b32 s72, s72, 1
	s_mul_i32 s6, s72, 12
	s_sub_i32 s70, s3, s6
